# speedup vs baseline: 1.0072x; 1.0072x over previous
; template <int TRM>
; DI void inproj_epi(const acc4 (&acc)[2][2][4][2], int wr, int wc, int fr, int fq, int pm, int pn, u16* R, u16* T, float* CB, u32* KMAX2, const float* bfp, char* lds) {
;     ...
;           for (int bj = 0; bj < 2; ++bj) {
;             const int cbase = pn * 256 + bj * 128 + wc * 32;
;             if (TRM & (1 << bj)) {
; #pragma unroll
;               for (int ai = 0; ai < 2; ++ai)
; #pragma unroll
;                 for (int m = 0; m < 4; ++m) {
;                   const int row = pm * 256 + ai * 128 + wr * 64 + m * 16 + fr;
; #pragma unroll
;                   for (int n = 0; n < 2; ++n) {
;                     const int col = cbase + n * 16 + fq * 4;
;                     const acc4 v = acc[ai][bj][m][n];
;                     u32x2 pk = {pack2(v[0], v[1]), pack2(v[2], v[3])};
;                     *reinterpret_cast<u32x2*>(R + (row * LDR + col)) = pk;
;                     if (col == RC_F) {
; #pragma unroll
;                       for (int j = 0; j < 4; ++j) CB[(size_t)j * SEQ + row] = v[j] + bfp[j];
;                     }
;                   }
;                 }
.LBB0_272:
	v_readlane_b32 s10, v255, 52
	s_lshl_b32 s10, s10, 8
	s_lshl_b32 s11, s22, 5
	s_or_b32 s10, s11, s10
	v_readlane_b32 s11, v255, 51
	v_lshl_or_b32 v132, v0, 2, s10
	s_movk_i32 s10, 0x880
	v_lshl_add_u32 v130, s11, 8, v130
	v_mul_lo_u32 v0, v130, s10
	v_and_b32_e32 v133, 16, v159
	v_lshrrev_b32_e32 v135, 2, v133
	v_sub_u32_e32 v133, v133, v135
	v_add_u32_e32 v131, v132, v133
	v_mov_b32_e32 v134, v0
	v_add_u32_e32 v136, v131, v134
	v_ashrrev_i32_e32 v137, 31, v136
	v_cvt_pk_bf16_f32 v200, v126, v127
	v_cvt_pk_bf16_f32 v201, v128, v129
	v_cvt_pk_bf16_f32 v202, v122, v123
	v_cvt_pk_bf16_f32 v203, v124, v125
	v_lshl_add_u64 v[136:137], v[136:137], 1, s[82:83]
	s_nop 0
	v_permlane16_swap_b32_e32 v200, v202
	v_permlane16_swap_b32_e32 v201, v203
	global_store_dwordx4 v[136:137], v[200:203], off
	v_add_u32_e32 v134, 0x8800, v134
	v_add_u32_e32 v136, v131, v134
	v_ashrrev_i32_e32 v137, 31, v136
	v_cvt_pk_bf16_f32 v204, v118, v119
	v_cvt_pk_bf16_f32 v205, v120, v121
	v_cvt_pk_bf16_f32 v206, v114, v115
	v_cvt_pk_bf16_f32 v207, v116, v117
	v_lshl_add_u64 v[136:137], v[136:137], 1, s[82:83]
	s_nop 0
	v_permlane16_swap_b32_e32 v204, v206
	v_permlane16_swap_b32_e32 v205, v207
	global_store_dwordx4 v[136:137], v[204:207], off
	v_add_u32_e32 v134, 0x8800, v134
	v_add_u32_e32 v136, v131, v134
	v_ashrrev_i32_e32 v137, 31, v136
	v_cvt_pk_bf16_f32 v200, v106, v107
	v_cvt_pk_bf16_f32 v201, v108, v109
	v_cvt_pk_bf16_f32 v202, v98, v99
	v_cvt_pk_bf16_f32 v203, v100, v101
	v_lshl_add_u64 v[136:137], v[136:137], 1, s[82:83]
	s_nop 0
	v_permlane16_swap_b32_e32 v200, v202
	v_permlane16_swap_b32_e32 v201, v203
	global_store_dwordx4 v[136:137], v[200:203], off
	v_add_u32_e32 v134, 0x8800, v134
	v_add_u32_e32 v136, v131, v134
	v_ashrrev_i32_e32 v137, 31, v136
	v_cvt_pk_bf16_f32 v204, v90, v91
	v_cvt_pk_bf16_f32 v205, v92, v93
	v_cvt_pk_bf16_f32 v206, v82, v83
	v_cvt_pk_bf16_f32 v207, v84, v85
	v_lshl_add_u64 v[136:137], v[136:137], 1, s[82:83]
	s_nop 0
	v_permlane16_swap_b32_e32 v204, v206
	v_permlane16_swap_b32_e32 v205, v207
	global_store_dwordx4 v[136:137], v[204:207], off
	v_add_u32_e32 v134, 0x2a800, v134
	v_add_u32_e32 v136, v131, v134
	v_ashrrev_i32_e32 v137, 31, v136
	v_cvt_pk_bf16_f32 v200, v110, v111
	v_cvt_pk_bf16_f32 v201, v112, v113
	v_cvt_pk_bf16_f32 v202, v102, v103
	v_cvt_pk_bf16_f32 v203, v104, v105
	v_lshl_add_u64 v[136:137], v[136:137], 1, s[82:83]
	s_nop 0
	v_permlane16_swap_b32_e32 v200, v202
	v_permlane16_swap_b32_e32 v201, v203
	global_store_dwordx4 v[136:137], v[200:203], off
	v_add_u32_e32 v134, 0x8800, v134
	v_add_u32_e32 v136, v131, v134
	v_ashrrev_i32_e32 v137, 31, v136
	v_cvt_pk_bf16_f32 v204, v94, v95
	v_cvt_pk_bf16_f32 v205, v96, v97
	v_cvt_pk_bf16_f32 v206, v86, v87
	v_cvt_pk_bf16_f32 v207, v88, v89
	v_lshl_add_u64 v[136:137], v[136:137], 1, s[82:83]
	s_nop 0
	v_permlane16_swap_b32_e32 v204, v206
	v_permlane16_swap_b32_e32 v205, v207
	global_store_dwordx4 v[136:137], v[204:207], off
	v_add_u32_e32 v134, 0x8800, v134
	v_add_u32_e32 v136, v131, v134
	v_ashrrev_i32_e32 v137, 31, v136
	v_cvt_pk_bf16_f32 v200, v78, v79
	v_cvt_pk_bf16_f32 v201, v80, v81
	v_cvt_pk_bf16_f32 v202, v74, v75
	v_cvt_pk_bf16_f32 v203, v76, v77
	v_lshl_add_u64 v[136:137], v[136:137], 1, s[82:83]
	s_nop 0
	v_permlane16_swap_b32_e32 v200, v202
	v_permlane16_swap_b32_e32 v201, v203
	global_store_dwordx4 v[136:137], v[200:203], off
	v_add_u32_e32 v134, 0x8800, v134
	v_add_u32_e32 v136, v131, v134
	v_ashrrev_i32_e32 v137, 31, v136
	v_cvt_pk_bf16_f32 v204, v70, v71
	v_cvt_pk_bf16_f32 v205, v72, v73
	v_cvt_pk_bf16_f32 v206, v66, v67
	v_cvt_pk_bf16_f32 v207, v68, v69
	v_lshl_add_u64 v[136:137], v[136:137], 1, s[82:83]
	s_nop 0
	v_permlane16_swap_b32_e32 v204, v206
	v_permlane16_swap_b32_e32 v205, v207
	global_store_dwordx4 v[136:137], v[204:207], off
	v_readlane_b32 s11, v255, 52
	s_cmp_eq_u32 s11, 7
	s_cselect_b32 s10, 8, 0
	s_cmp_gt_i32 s11, 6
	s_mov_b64 s[44:45], -1
	s_cbranch_scc1 .LBB0_290
	v_readlane_b32 s11, v255, 52
	s_cmp_eq_u32 s11, 5
	s_cselect_b64 s[44:45], -1, 0

; template <int TRM>
; DI void inproj_epi(const acc4 (&acc)[2][2][4][2], int wr, int wc, int fr, int fq, int pm, int pn, u16* R, u16* T, float* CB, u32* KMAX2, const float* bfp, char* lds) {
;     ...
;           for (int bj = 0; bj < 2; ++bj) {
;             const int cbase = pn * 256 + bj * 128 + wc * 32;
;             if (TRM & (1 << bj)) {
; #pragma unroll
;               for (int ai = 0; ai < 2; ++ai)
; #pragma unroll
;                 for (int m = 0; m < 4; ++m) {
;                   const int row = pm * 256 + ai * 128 + wr * 64 + m * 16 + fr;
; #pragma unroll
;                   for (int n = 0; n < 2; ++n) {
;                     const int col = cbase + n * 16 + fq * 4;
;                     const acc4 v = acc[ai][bj][m][n];
;                     u32x2 pk = {pack2(v[0], v[1]), pack2(v[2], v[3])};
;                     *reinterpret_cast<u32x2*>(R + (row * LDR + col)) = pk;
;                     if (col == RC_F) {
; #pragma unroll
;                       for (int j = 0; j < 4; ++j) CB[(size_t)j * SEQ + row] = v[j] + bfp[j];
;                     }
;                   }
;                 }
.LBB0_297:
	s_waitcnt lgkmcnt(0)
	v_and_b32_e32 v133, 16, v159
	v_lshrrev_b32_e32 v135, 2, v133
	v_sub_u32_e32 v133, v133, v135
	v_or_b32_e32 v70, 0x80, v132
	v_add_u32_e32 v70, v70, v133
	v_mov_b32_e32 v134, v0
	v_add_u32_e32 v136, v70, v134
	v_ashrrev_i32_e32 v137, 31, v136
	v_cvt_pk_bf16_f32 v200, v62, v63
	v_cvt_pk_bf16_f32 v201, v64, v65
	v_cvt_pk_bf16_f32 v202, v58, v59
	v_cvt_pk_bf16_f32 v203, v60, v61
	v_lshl_add_u64 v[136:137], v[136:137], 1, s[82:83]
	s_nop 0
	v_permlane16_swap_b32_e32 v200, v202
	v_permlane16_swap_b32_e32 v201, v203
	global_store_dwordx4 v[136:137], v[200:203], off
	v_add_u32_e32 v134, 0x8800, v134
	v_add_u32_e32 v136, v70, v134
	v_ashrrev_i32_e32 v137, 31, v136
	v_cvt_pk_bf16_f32 v204, v54, v55
	v_cvt_pk_bf16_f32 v205, v56, v57
	v_cvt_pk_bf16_f32 v206, v50, v51
	v_cvt_pk_bf16_f32 v207, v52, v53
	v_lshl_add_u64 v[136:137], v[136:137], 1, s[82:83]
	s_nop 0
	v_permlane16_swap_b32_e32 v204, v206
	v_permlane16_swap_b32_e32 v205, v207
	global_store_dwordx4 v[136:137], v[204:207], off
	v_add_u32_e32 v134, 0x8800, v134
	v_add_u32_e32 v136, v70, v134
	v_ashrrev_i32_e32 v137, 31, v136
	v_cvt_pk_bf16_f32 v200, v46, v47
	v_cvt_pk_bf16_f32 v201, v48, v49
	v_cvt_pk_bf16_f32 v202, v38, v39
	v_cvt_pk_bf16_f32 v203, v40, v41
	v_lshl_add_u64 v[136:137], v[136:137], 1, s[82:83]
	s_nop 0
	v_permlane16_swap_b32_e32 v200, v202
	v_permlane16_swap_b32_e32 v201, v203
	global_store_dwordx4 v[136:137], v[200:203], off
	v_add_u32_e32 v134, 0x8800, v134
	v_add_u32_e32 v136, v70, v134
	v_ashrrev_i32_e32 v137, 31, v136
	v_cvt_pk_bf16_f32 v204, v30, v31
	v_cvt_pk_bf16_f32 v205, v32, v33
	v_cvt_pk_bf16_f32 v206, v26, v27
	v_cvt_pk_bf16_f32 v207, v28, v29
	v_lshl_add_u64 v[136:137], v[136:137], 1, s[82:83]
	s_nop 0
	v_permlane16_swap_b32_e32 v204, v206
	v_permlane16_swap_b32_e32 v205, v207
	global_store_dwordx4 v[136:137], v[204:207], off
	v_add_u32_e32 v134, 0x2a800, v134
	v_add_u32_e32 v136, v70, v134
	v_ashrrev_i32_e32 v137, 31, v136
	v_cvt_pk_bf16_f32 v200, v42, v43
	v_cvt_pk_bf16_f32 v201, v44, v45
	v_cvt_pk_bf16_f32 v202, v34, v35
	v_cvt_pk_bf16_f32 v203, v36, v37
	v_lshl_add_u64 v[136:137], v[136:137], 1, s[82:83]
	s_nop 0
	v_permlane16_swap_b32_e32 v200, v202
	v_permlane16_swap_b32_e32 v201, v203
	global_store_dwordx4 v[136:137], v[200:203], off
	v_add_u32_e32 v134, 0x8800, v134
	v_add_u32_e32 v136, v70, v134
	v_ashrrev_i32_e32 v137, 31, v136
	v_cvt_pk_bf16_f32 v204, v22, v23
	v_cvt_pk_bf16_f32 v205, v24, v25
	v_cvt_pk_bf16_f32 v206, v18, v19
	v_cvt_pk_bf16_f32 v207, v20, v21
	v_lshl_add_u64 v[136:137], v[136:137], 1, s[82:83]
	s_nop 0
	v_permlane16_swap_b32_e32 v204, v206
	v_permlane16_swap_b32_e32 v205, v207
	global_store_dwordx4 v[136:137], v[204:207], off
	v_add_u32_e32 v134, 0x8800, v134
	v_add_u32_e32 v136, v70, v134
	v_ashrrev_i32_e32 v137, 31, v136
	v_cvt_pk_bf16_f32 v200, v14, v15
	v_cvt_pk_bf16_f32 v201, v16, v17
	v_cvt_pk_bf16_f32 v202, v10, v11
	v_cvt_pk_bf16_f32 v203, v12, v13
	v_lshl_add_u64 v[136:137], v[136:137], 1, s[82:83]
	s_nop 0
	v_permlane16_swap_b32_e32 v200, v202
	v_permlane16_swap_b32_e32 v201, v203
	global_store_dwordx4 v[136:137], v[200:203], off
	v_add_u32_e32 v134, 0x8800, v134
	v_add_u32_e32 v136, v70, v134
	v_ashrrev_i32_e32 v137, 31, v136
	v_cvt_pk_bf16_f32 v204, v6, v7
	v_cvt_pk_bf16_f32 v205, v8, v9
	v_cvt_pk_bf16_f32 v206, v2, v3
	v_cvt_pk_bf16_f32 v207, v4, v5
	v_lshl_add_u64 v[136:137], v[136:137], 1, s[82:83]
	s_nop 0
	v_permlane16_swap_b32_e32 v204, v206
	v_permlane16_swap_b32_e32 v205, v207
	global_store_dwordx4 v[136:137], v[204:207], off
	v_readlane_b32 s11, v255, 52
	s_cmp_gt_i32 s11, 6
	s_mov_b64 s[44:45], -1
	s_cbranch_scc1 .LBB0_299
	v_readlane_b32 s11, v255, 52
	s_cmp_eq_u32 s11, 5
	s_cselect_b64 s[44:45], -1, 0
